# diff attention loop: cross-half row max via v_permlane32_swap instead of ds_bpermute
# baseline (speedup 1.0000x reference)
.LBB0_481:
	s_or_b64 exec, exec, s[0:1]
	s_nop 5
	v_mul_f32_e32 v170, v137, v82
	s_nop 0
	v_mul_f32_e32 v171, v137, v66
	v_max3_f32 v170, v170, v171, v83
	v_max_f32_e32 v171, v81, v81
	v_max3_f32 v170, v170, v67, v84
	v_and_b32_e32 v172, 64, v211
	v_max3_f32 v170, v170, v68, v85
	v_add_u32_e32 v172, 64, v172
	v_max3_f32 v170, v170, v69, v86
	v_cndmask_b32_e32 v0, 0, v149, vcc
	v_max3_f32 v170, v170, v70, v87
	s_mov_b32 s0, 0x41200000
	v_max3_f32 v170, v170, v71, v88
	s_nop 0
	v_max3_f32 v170, v170, v72, v89
	s_nop 0
	v_max3_f32 v170, v170, v73, v90
	s_nop 0
	v_max3_f32 v170, v170, v74, v91
	s_nop 0
	v_max3_f32 v170, v170, v75, v92
	s_nop 0
	v_max3_f32 v170, v170, v76, v93
	s_nop 0
	v_max3_f32 v170, v170, v77, v94
	s_nop 0
	v_max3_f32 v170, v170, v78, v95
	s_nop 0
	v_max3_f32 v170, v170, v79, v96
	s_nop 0
	v_max3_f32 v170, v170, v80, v97
	s_nop 0
	v_max_f32_e32 v170, v170, v170
	v_max_f32_e32 v170, v170, v171
	v_mov_b32_e32 v171, v170
	s_nop 1
	v_permlane32_swap_b32_e32 v171, v170
	v_max_f32_e32 v170, v170, v171
	v_add_f32_e32 v170, v0, v170
	v_sub_f32_e32 v171, v170, v150
	v_cmp_lt_f32_e32 vcc, s0, v171
	s_cbranch_vccz .LBB0_483
	v_max_f32_e32 v170, v170, v170
	v_max_f32_e32 v171, v150, v150
	v_max_f32_e32 v170, v171, v170
	v_sub_f32_e32 v150, v150, v170
	v_exp_f32_e32 v150, v150
	s_nop 0
	v_pk_mul_f32 v[64:65], v[64:65], v[150:151] op_sel_hi:[1,0]
	v_pk_mul_f32 v[62:63], v[62:63], v[150:151] op_sel_hi:[1,0]
	v_pk_mul_f32 v[60:61], v[60:61], v[150:151] op_sel_hi:[1,0]
	v_pk_mul_f32 v[58:59], v[58:59], v[150:151] op_sel_hi:[1,0]
	v_pk_mul_f32 v[56:57], v[56:57], v[150:151] op_sel_hi:[1,0]
	v_pk_mul_f32 v[54:55], v[54:55], v[150:151] op_sel_hi:[1,0]
	v_pk_mul_f32 v[52:53], v[52:53], v[150:151] op_sel_hi:[1,0]
	v_pk_mul_f32 v[50:51], v[50:51], v[150:151] op_sel_hi:[1,0]
	v_pk_mul_f32 v[48:49], v[48:49], v[150:151] op_sel_hi:[1,0]
	v_pk_mul_f32 v[46:47], v[46:47], v[150:151] op_sel_hi:[1,0]
	v_pk_mul_f32 v[44:45], v[44:45], v[150:151] op_sel_hi:[1,0]
	v_pk_mul_f32 v[42:43], v[42:43], v[150:151] op_sel_hi:[1,0]
	v_pk_mul_f32 v[40:41], v[40:41], v[150:151] op_sel_hi:[1,0]
	v_pk_mul_f32 v[38:39], v[38:39], v[150:151] op_sel_hi:[1,0]
	v_pk_mul_f32 v[36:37], v[36:37], v[150:151] op_sel_hi:[1,0]
	v_pk_mul_f32 v[34:35], v[34:35], v[150:151] op_sel_hi:[1,0]
	v_pk_mul_f32 v[32:33], v[32:33], v[150:151] op_sel_hi:[1,0]
	v_pk_mul_f32 v[30:31], v[30:31], v[150:151] op_sel_hi:[1,0]
	v_pk_mul_f32 v[28:29], v[28:29], v[150:151] op_sel_hi:[1,0]
	v_pk_mul_f32 v[26:27], v[26:27], v[150:151] op_sel_hi:[1,0]
	v_pk_mul_f32 v[24:25], v[24:25], v[150:151] op_sel_hi:[1,0]
	v_pk_mul_f32 v[22:23], v[22:23], v[150:151] op_sel_hi:[1,0]
	v_pk_mul_f32 v[20:21], v[20:21], v[150:151] op_sel_hi:[1,0]
	v_pk_mul_f32 v[18:19], v[18:19], v[150:151] op_sel_hi:[1,0]
	v_pk_mul_f32 v[16:17], v[16:17], v[150:151] op_sel_hi:[1,0]
	v_pk_mul_f32 v[14:15], v[14:15], v[150:151] op_sel_hi:[1,0]
	v_pk_mul_f32 v[12:13], v[12:13], v[150:151] op_sel_hi:[1,0]
	v_pk_mul_f32 v[10:11], v[10:11], v[150:151] op_sel_hi:[1,0]
	v_pk_mul_f32 v[8:9], v[8:9], v[150:151] op_sel_hi:[1,0]
	v_pk_mul_f32 v[6:7], v[6:7], v[150:151] op_sel_hi:[1,0]
	v_pk_mul_f32 v[4:5], v[4:5], v[150:151] op_sel_hi:[1,0]
	v_pk_mul_f32 v[2:3], v[2:3], v[150:151] op_sel_hi:[1,0]
	v_mul_f32_e32 v131, v131, v150
	v_mov_b32_e32 v150, v170
